# rstd_finalize partial-sum loops unrolled: 16 loads in flight behind one wait instead of load-wait-add per partial (before G1 and G3, every layer); bit-identical
# baseline (speedup 1.0000x reference)
; __device__ __forceinline__ void rstd_finalize(const float* __restrict__ part, int pm, int np, LAS float* rstd_l) {
;     ...
;     const int row = t >> 1, half = t & 1, pa = half ? (np + 1) / 2 : 0, pb = half ? np : (np + 1) / 2;
;     const float* p = part + (size_t)pm * 32 * 256 + row; float s = 0.f;
;     for (int i = pa; i < pb; ++i) s += p[i * 256];
;     s += __shfl_xor(s, 1);
;     if (half == 0) rstd_l[row] = 1.0f / sqrtf(s * (1.f / DM) + EPS);
.LBB0_125:
	v_mov_b32_e32 v8, 0
	v_mov_b32_e32 v9, 0
	v_mov_b32_e32 v10, 0
	v_mov_b32_e32 v11, 0
	v_mov_b32_e32 v12, 0
	v_mov_b32_e32 v13, 0
	v_mov_b32_e32 v14, 0
	v_mov_b32_e32 v15, 0
	v_mov_b32_e32 v16, 0
	v_mov_b32_e32 v17, 0
	v_mov_b32_e32 v18, 0
	v_mov_b32_e32 v19, 0
	v_mov_b32_e32 v20, 0
	v_mov_b32_e32 v21, 0
	v_mov_b32_e32 v22, 0
	v_mov_b32_e32 v23, 0
	global_load_dword v8, v[2:3], off
	v_add_u32_e32 v5, 1, v5
	v_cmp_ge_u32_e64 s[38:39], v5, v6
	v_lshl_add_u64 v[2:3], v[2:3], 0, s[34:35]
	s_or_b64 s[28:29], s[38:39], s[28:29]
	s_andn2_b64 exec, exec, s[28:29]
	s_cbranch_execz .Lrf_done_g1
	global_load_dword v9, v[2:3], off
	v_add_u32_e32 v5, 1, v5
	v_cmp_ge_u32_e64 s[38:39], v5, v6
	v_lshl_add_u64 v[2:3], v[2:3], 0, s[34:35]
	s_or_b64 s[28:29], s[38:39], s[28:29]
	s_andn2_b64 exec, exec, s[28:29]
	s_cbranch_execz .Lrf_done_g1
	global_load_dword v10, v[2:3], off
	v_add_u32_e32 v5, 1, v5
	v_cmp_ge_u32_e64 s[38:39], v5, v6
	v_lshl_add_u64 v[2:3], v[2:3], 0, s[34:35]
	s_or_b64 s[28:29], s[38:39], s[28:29]
	s_andn2_b64 exec, exec, s[28:29]
	s_cbranch_execz .Lrf_done_g1
	global_load_dword v11, v[2:3], off
	v_add_u32_e32 v5, 1, v5
	v_cmp_ge_u32_e64 s[38:39], v5, v6
	v_lshl_add_u64 v[2:3], v[2:3], 0, s[34:35]
	s_or_b64 s[28:29], s[38:39], s[28:29]
	s_andn2_b64 exec, exec, s[28:29]
	s_cbranch_execz .Lrf_done_g1
	global_load_dword v12, v[2:3], off
	v_add_u32_e32 v5, 1, v5
	v_cmp_ge_u32_e64 s[38:39], v5, v6
	v_lshl_add_u64 v[2:3], v[2:3], 0, s[34:35]
	s_or_b64 s[28:29], s[38:39], s[28:29]
	s_andn2_b64 exec, exec, s[28:29]
	s_cbranch_execz .Lrf_done_g1
	global_load_dword v13, v[2:3], off
	v_add_u32_e32 v5, 1, v5
	v_cmp_ge_u32_e64 s[38:39], v5, v6
	v_lshl_add_u64 v[2:3], v[2:3], 0, s[34:35]
	s_or_b64 s[28:29], s[38:39], s[28:29]
	s_andn2_b64 exec, exec, s[28:29]
	s_cbranch_execz .Lrf_done_g1
	global_load_dword v14, v[2:3], off
	v_add_u32_e32 v5, 1, v5
	v_cmp_ge_u32_e64 s[38:39], v5, v6
	v_lshl_add_u64 v[2:3], v[2:3], 0, s[34:35]
	s_or_b64 s[28:29], s[38:39], s[28:29]
	s_andn2_b64 exec, exec, s[28:29]
	s_cbranch_execz .Lrf_done_g1
	global_load_dword v15, v[2:3], off
	v_add_u32_e32 v5, 1, v5
	v_cmp_ge_u32_e64 s[38:39], v5, v6
	v_lshl_add_u64 v[2:3], v[2:3], 0, s[34:35]
	s_or_b64 s[28:29], s[38:39], s[28:29]
	s_andn2_b64 exec, exec, s[28:29]
	s_cbranch_execz .Lrf_done_g1
	global_load_dword v16, v[2:3], off
	v_add_u32_e32 v5, 1, v5
	v_cmp_ge_u32_e64 s[38:39], v5, v6
	v_lshl_add_u64 v[2:3], v[2:3], 0, s[34:35]
	s_or_b64 s[28:29], s[38:39], s[28:29]
	s_andn2_b64 exec, exec, s[28:29]
	s_cbranch_execz .Lrf_done_g1
	global_load_dword v17, v[2:3], off
	v_add_u32_e32 v5, 1, v5
	v_cmp_ge_u32_e64 s[38:39], v5, v6
	v_lshl_add_u64 v[2:3], v[2:3], 0, s[34:35]
	s_or_b64 s[28:29], s[38:39], s[28:29]
	s_andn2_b64 exec, exec, s[28:29]
	s_cbranch_execz .Lrf_done_g1
	global_load_dword v18, v[2:3], off
	v_add_u32_e32 v5, 1, v5
	v_cmp_ge_u32_e64 s[38:39], v5, v6
	v_lshl_add_u64 v[2:3], v[2:3], 0, s[34:35]
	s_or_b64 s[28:29], s[38:39], s[28:29]
	s_andn2_b64 exec, exec, s[28:29]
	s_cbranch_execz .Lrf_done_g1
	global_load_dword v19, v[2:3], off
	v_add_u32_e32 v5, 1, v5
	v_cmp_ge_u32_e64 s[38:39], v5, v6
	v_lshl_add_u64 v[2:3], v[2:3], 0, s[34:35]
	s_or_b64 s[28:29], s[38:39], s[28:29]
	s_andn2_b64 exec, exec, s[28:29]
	s_cbranch_execz .Lrf_done_g1
	global_load_dword v20, v[2:3], off
	v_add_u32_e32 v5, 1, v5
	v_cmp_ge_u32_e64 s[38:39], v5, v6
	v_lshl_add_u64 v[2:3], v[2:3], 0, s[34:35]
	s_or_b64 s[28:29], s[38:39], s[28:29]
	s_andn2_b64 exec, exec, s[28:29]
	s_cbranch_execz .Lrf_done_g1
	global_load_dword v21, v[2:3], off
	v_add_u32_e32 v5, 1, v5
	v_cmp_ge_u32_e64 s[38:39], v5, v6
	v_lshl_add_u64 v[2:3], v[2:3], 0, s[34:35]
	s_or_b64 s[28:29], s[38:39], s[28:29]
	s_andn2_b64 exec, exec, s[28:29]
	s_cbranch_execz .Lrf_done_g1
	global_load_dword v22, v[2:3], off
	v_add_u32_e32 v5, 1, v5
	v_cmp_ge_u32_e64 s[38:39], v5, v6
	v_lshl_add_u64 v[2:3], v[2:3], 0, s[34:35]
	s_or_b64 s[28:29], s[38:39], s[28:29]
	s_andn2_b64 exec, exec, s[28:29]
	s_cbranch_execz .Lrf_done_g1
	global_load_dword v23, v[2:3], off
	v_add_u32_e32 v5, 1, v5
	v_cmp_ge_u32_e64 s[38:39], v5, v6
	v_lshl_add_u64 v[2:3], v[2:3], 0, s[34:35]
	s_or_b64 s[28:29], s[38:39], s[28:29]
	s_andn2_b64 exec, exec, s[28:29]
.Lrf_done_g1:
	s_or_b64 exec, exec, s[28:29]
	s_waitcnt vmcnt(0)
	v_add_f32_e32 v4, v4, v8
	v_add_f32_e32 v4, v4, v9
	v_add_f32_e32 v4, v4, v10
	v_add_f32_e32 v4, v4, v11
	v_add_f32_e32 v4, v4, v12
	v_add_f32_e32 v4, v4, v13
	v_add_f32_e32 v4, v4, v14
	v_add_f32_e32 v4, v4, v15
	v_add_f32_e32 v4, v4, v16
	v_add_f32_e32 v4, v4, v17
	v_add_f32_e32 v4, v4, v18
	v_add_f32_e32 v4, v4, v19
	v_add_f32_e32 v4, v4, v20
	v_add_f32_e32 v4, v4, v21
	v_add_f32_e32 v4, v4, v22
	v_add_f32_e32 v4, v4, v23

; __device__ __forceinline__ void rstd_finalize(const float* __restrict__ part, int pm, int np, LAS float* rstd_l) {
;     ...
;     const int row = t >> 1, half = t & 1, pa = half ? (np + 1) / 2 : 0, pb = half ? np : (np + 1) / 2;
;     const float* p = part + (size_t)pm * 32 * 256 + row; float s = 0.f;
;     for (int i = pa; i < pb; ++i) s += p[i * 256];
.LBB0_355:
	v_mov_b32_e32 v8, 0
	v_mov_b32_e32 v9, 0
	v_mov_b32_e32 v10, 0
	v_mov_b32_e32 v11, 0
	v_mov_b32_e32 v12, 0
	v_mov_b32_e32 v13, 0
	v_mov_b32_e32 v14, 0
	v_mov_b32_e32 v15, 0
	v_mov_b32_e32 v16, 0
	v_mov_b32_e32 v17, 0
	v_mov_b32_e32 v18, 0
	v_mov_b32_e32 v19, 0
	v_mov_b32_e32 v20, 0
	v_mov_b32_e32 v21, 0
	v_mov_b32_e32 v22, 0
	v_mov_b32_e32 v23, 0
	global_load_dword v8, v[2:3], off
	v_add_u32_e32 v5, 1, v5
	v_cmp_ge_u32_e64 s[42:43], v5, v6
	v_lshl_add_u64 v[2:3], v[2:3], 0, s[34:35]
	s_or_b64 s[28:29], s[42:43], s[28:29]
	s_andn2_b64 exec, exec, s[28:29]
	s_cbranch_execz .Lrf_done_g3
	global_load_dword v9, v[2:3], off
	v_add_u32_e32 v5, 1, v5
	v_cmp_ge_u32_e64 s[42:43], v5, v6
	v_lshl_add_u64 v[2:3], v[2:3], 0, s[34:35]
	s_or_b64 s[28:29], s[42:43], s[28:29]
	s_andn2_b64 exec, exec, s[28:29]
	s_cbranch_execz .Lrf_done_g3
	global_load_dword v10, v[2:3], off
	v_add_u32_e32 v5, 1, v5
	v_cmp_ge_u32_e64 s[42:43], v5, v6
	v_lshl_add_u64 v[2:3], v[2:3], 0, s[34:35]
	s_or_b64 s[28:29], s[42:43], s[28:29]
	s_andn2_b64 exec, exec, s[28:29]
	s_cbranch_execz .Lrf_done_g3
	global_load_dword v11, v[2:3], off
	v_add_u32_e32 v5, 1, v5
	v_cmp_ge_u32_e64 s[42:43], v5, v6
	v_lshl_add_u64 v[2:3], v[2:3], 0, s[34:35]
	s_or_b64 s[28:29], s[42:43], s[28:29]
	s_andn2_b64 exec, exec, s[28:29]
	s_cbranch_execz .Lrf_done_g3
	global_load_dword v12, v[2:3], off
	v_add_u32_e32 v5, 1, v5
	v_cmp_ge_u32_e64 s[42:43], v5, v6
	v_lshl_add_u64 v[2:3], v[2:3], 0, s[34:35]
	s_or_b64 s[28:29], s[42:43], s[28:29]
	s_andn2_b64 exec, exec, s[28:29]
	s_cbranch_execz .Lrf_done_g3
	global_load_dword v13, v[2:3], off
	v_add_u32_e32 v5, 1, v5
	v_cmp_ge_u32_e64 s[42:43], v5, v6
	v_lshl_add_u64 v[2:3], v[2:3], 0, s[34:35]
	s_or_b64 s[28:29], s[42:43], s[28:29]
	s_andn2_b64 exec, exec, s[28:29]
	s_cbranch_execz .Lrf_done_g3
	global_load_dword v14, v[2:3], off
	v_add_u32_e32 v5, 1, v5
	v_cmp_ge_u32_e64 s[42:43], v5, v6
	v_lshl_add_u64 v[2:3], v[2:3], 0, s[34:35]
	s_or_b64 s[28:29], s[42:43], s[28:29]
	s_andn2_b64 exec, exec, s[28:29]
	s_cbranch_execz .Lrf_done_g3
	global_load_dword v15, v[2:3], off
	v_add_u32_e32 v5, 1, v5
	v_cmp_ge_u32_e64 s[42:43], v5, v6
	v_lshl_add_u64 v[2:3], v[2:3], 0, s[34:35]
	s_or_b64 s[28:29], s[42:43], s[28:29]
	s_andn2_b64 exec, exec, s[28:29]
	s_cbranch_execz .Lrf_done_g3
	global_load_dword v16, v[2:3], off
	v_add_u32_e32 v5, 1, v5
	v_cmp_ge_u32_e64 s[42:43], v5, v6
	v_lshl_add_u64 v[2:3], v[2:3], 0, s[34:35]
	s_or_b64 s[28:29], s[42:43], s[28:29]
	s_andn2_b64 exec, exec, s[28:29]
	s_cbranch_execz .Lrf_done_g3
	global_load_dword v17, v[2:3], off
	v_add_u32_e32 v5, 1, v5
	v_cmp_ge_u32_e64 s[42:43], v5, v6
	v_lshl_add_u64 v[2:3], v[2:3], 0, s[34:35]
	s_or_b64 s[28:29], s[42:43], s[28:29]
	s_andn2_b64 exec, exec, s[28:29]
	s_cbranch_execz .Lrf_done_g3
	global_load_dword v18, v[2:3], off
	v_add_u32_e32 v5, 1, v5
	v_cmp_ge_u32_e64 s[42:43], v5, v6
	v_lshl_add_u64 v[2:3], v[2:3], 0, s[34:35]
	s_or_b64 s[28:29], s[42:43], s[28:29]
	s_andn2_b64 exec, exec, s[28:29]
	s_cbranch_execz .Lrf_done_g3
	global_load_dword v19, v[2:3], off
	v_add_u32_e32 v5, 1, v5
	v_cmp_ge_u32_e64 s[42:43], v5, v6
	v_lshl_add_u64 v[2:3], v[2:3], 0, s[34:35]
	s_or_b64 s[28:29], s[42:43], s[28:29]
	s_andn2_b64 exec, exec, s[28:29]
	s_cbranch_execz .Lrf_done_g3
	global_load_dword v20, v[2:3], off
	v_add_u32_e32 v5, 1, v5
	v_cmp_ge_u32_e64 s[42:43], v5, v6
	v_lshl_add_u64 v[2:3], v[2:3], 0, s[34:35]
	s_or_b64 s[28:29], s[42:43], s[28:29]
	s_andn2_b64 exec, exec, s[28:29]
	s_cbranch_execz .Lrf_done_g3
	global_load_dword v21, v[2:3], off
	v_add_u32_e32 v5, 1, v5
	v_cmp_ge_u32_e64 s[42:43], v5, v6
	v_lshl_add_u64 v[2:3], v[2:3], 0, s[34:35]
	s_or_b64 s[28:29], s[42:43], s[28:29]
	s_andn2_b64 exec, exec, s[28:29]
	s_cbranch_execz .Lrf_done_g3
	global_load_dword v22, v[2:3], off
	v_add_u32_e32 v5, 1, v5
	v_cmp_ge_u32_e64 s[42:43], v5, v6
	v_lshl_add_u64 v[2:3], v[2:3], 0, s[34:35]
	s_or_b64 s[28:29], s[42:43], s[28:29]
	s_andn2_b64 exec, exec, s[28:29]
	s_cbranch_execz .Lrf_done_g3
	global_load_dword v23, v[2:3], off
	v_add_u32_e32 v5, 1, v5
	v_cmp_ge_u32_e64 s[42:43], v5, v6
	v_lshl_add_u64 v[2:3], v[2:3], 0, s[34:35]
	s_or_b64 s[28:29], s[42:43], s[28:29]
	s_andn2_b64 exec, exec, s[28:29]
